# stack, barrier 1-5 hand-written: last leader releases all 16 XCD generation words (no TOPGEN relay hop)
# speedup vs baseline: 1.0273x; 1.0001x over previous
.LBB0_220:
	s_cmp_gt_i32 s83, 2
	s_cselect_b64 s[0:1], -1, 0
	s_and_b64 s[4:5], s[28:29], s[0:1]
	s_andn2_b64 vcc, exec, s[4:5]
	s_cbranch_vccnz .LBB0_274
	s_waitcnt vmcnt(0)
	s_waitcnt vmcnt(0)
	s_barrier
	s_and_saveexec_b64 s[4:5], s[94:95]
	s_cbranch_execz .LBB0_273
	v_mov_b32_e32 v1, 0x23ff0
	ds_read_b32 v2, v1
	ds_read_b32 v3, v1 offset:4
	s_add_u32 s6, s80, 0x2380000
	s_addc_u32 s7, s81, 0
	s_lshl_b32 s8, s87, 8
	s_add_i32 s9, s8, 0x1400
	s_add_i32 s8, s8, 0x2400
	v_mov_b32_e32 v4, s9
	v_mov_b32_e32 v5, 1
	global_atomic_add v6, v4, v5, s[6:7] sc0
	buffer_inv sc1
	s_waitcnt vmcnt(0) lgkmcnt(0)
	v_readfirstlane_b32 s10, v6
	v_readfirstlane_b32 s11, v2
	v_readfirstlane_b32 s16, v3
	s_add_i32 s10, s10, 1
	s_mul_i32 s11, s11, 2
	s_cmp_lg_u32 s10, s11
	s_cbranch_scc1 .Lxb_nl_1
	buffer_wbl2 sc1
	s_waitcnt vmcnt(0)
	v_mov_b32_e32 v4, 0x3400
	global_atomic_add v6, v4, v5, s[6:7] sc0
	s_waitcnt vmcnt(0)
	v_readfirstlane_b32 s10, v6
	s_add_i32 s10, s10, 1
	s_mul_i32 s16, s16, 2
	s_cmp_lg_u32 s10, s16
	s_cbranch_scc1 .Lxb_nl_1
	v_mov_b32_e32 v4, 0x2400
	global_atomic_add v4, v5, s[6:7]
	global_atomic_add v4, v5, s[6:7] offset:256
	global_atomic_add v4, v5, s[6:7] offset:512
	global_atomic_add v4, v5, s[6:7] offset:768
	global_atomic_add v4, v5, s[6:7] offset:1024
	global_atomic_add v4, v5, s[6:7] offset:1280
	global_atomic_add v4, v5, s[6:7] offset:1536
	global_atomic_add v4, v5, s[6:7] offset:1792
	global_atomic_add v4, v5, s[6:7] offset:2048
	global_atomic_add v4, v5, s[6:7] offset:2304
	global_atomic_add v4, v5, s[6:7] offset:2560
	global_atomic_add v4, v5, s[6:7] offset:2816
	global_atomic_add v4, v5, s[6:7] offset:3072
	global_atomic_add v4, v5, s[6:7] offset:3328
	global_atomic_add v4, v5, s[6:7] offset:3584
	global_atomic_add v4, v5, s[6:7] offset:3840
	s_branch .Lxb_done_1

.LBB0_349:
	s_cmp_gt_i32 s83, 3
	s_cselect_b64 s[0:1], -1, 0
	s_and_b64 s[4:5], s[18:19], s[0:1]
	s_andn2_b64 vcc, exec, s[4:5]
	s_cbranch_vccnz .LBB0_403
	s_waitcnt vmcnt(0)
	s_waitcnt vmcnt(0)
	s_barrier
	s_and_saveexec_b64 s[4:5], s[94:95]
	s_cbranch_execz .LBB0_402
	v_mov_b32_e32 v1, 0x23ff0
	ds_read_b32 v2, v1
	ds_read_b32 v3, v1 offset:4
	s_add_u32 s6, s80, 0x2380000
	s_addc_u32 s7, s81, 0
	s_lshl_b32 s8, s87, 8
	s_add_i32 s9, s8, 0x1400
	s_add_i32 s8, s8, 0x2400
	v_mov_b32_e32 v4, s9
	v_mov_b32_e32 v5, 1
	global_atomic_add v6, v4, v5, s[6:7] sc0
	buffer_inv sc1
	s_waitcnt vmcnt(0) lgkmcnt(0)
	v_readfirstlane_b32 s10, v6
	v_readfirstlane_b32 s11, v2
	v_readfirstlane_b32 s16, v3
	s_add_i32 s10, s10, 1
	s_mul_i32 s11, s11, 3
	s_cmp_lg_u32 s10, s11
	s_cbranch_scc1 .Lxb_nl_2
	buffer_wbl2 sc1
	s_waitcnt vmcnt(0)
	v_mov_b32_e32 v4, 0x3400
	global_atomic_add v6, v4, v5, s[6:7] sc0
	s_waitcnt vmcnt(0)
	v_readfirstlane_b32 s10, v6
	s_add_i32 s10, s10, 1
	s_mul_i32 s16, s16, 3
	s_cmp_lg_u32 s10, s16
	s_cbranch_scc1 .Lxb_nl_2
	v_mov_b32_e32 v4, 0x2400
	global_atomic_add v4, v5, s[6:7]
	global_atomic_add v4, v5, s[6:7] offset:256
	global_atomic_add v4, v5, s[6:7] offset:512
	global_atomic_add v4, v5, s[6:7] offset:768
	global_atomic_add v4, v5, s[6:7] offset:1024
	global_atomic_add v4, v5, s[6:7] offset:1280
	global_atomic_add v4, v5, s[6:7] offset:1536
	global_atomic_add v4, v5, s[6:7] offset:1792
	global_atomic_add v4, v5, s[6:7] offset:2048
	global_atomic_add v4, v5, s[6:7] offset:2304
	global_atomic_add v4, v5, s[6:7] offset:2560
	global_atomic_add v4, v5, s[6:7] offset:2816
	global_atomic_add v4, v5, s[6:7] offset:3072
	global_atomic_add v4, v5, s[6:7] offset:3328
	global_atomic_add v4, v5, s[6:7] offset:3584
	global_atomic_add v4, v5, s[6:7] offset:3840
	s_branch .Lxb_done_2

.LBB0_434:
	s_cmp_gt_i32 s83, 4
	s_cselect_b64 s[0:1], -1, 0
	s_and_b64 s[4:5], s[6:7], s[0:1]
	s_andn2_b64 vcc, exec, s[4:5]
	s_cbranch_vccnz .LBB0_488
	s_waitcnt vmcnt(0)
	s_waitcnt vmcnt(0)
	s_barrier
	s_and_saveexec_b64 s[4:5], s[94:95]
	s_cbranch_execz .LBB0_487
	v_mov_b32_e32 v1, 0x23ff0
	ds_read_b32 v2, v1
	ds_read_b32 v3, v1 offset:4
	s_add_u32 s6, s80, 0x2380000
	s_addc_u32 s7, s81, 0
	s_lshl_b32 s8, s87, 8
	s_add_i32 s9, s8, 0x1400
	s_add_i32 s8, s8, 0x2400
	v_mov_b32_e32 v4, s9
	v_mov_b32_e32 v5, 1
	global_atomic_add v6, v4, v5, s[6:7] sc0
	buffer_inv sc1
	s_waitcnt vmcnt(0) lgkmcnt(0)
	v_readfirstlane_b32 s10, v6
	v_readfirstlane_b32 s11, v2
	v_readfirstlane_b32 s16, v3
	s_add_i32 s10, s10, 1
	s_mul_i32 s11, s11, 4
	s_cmp_lg_u32 s10, s11
	s_cbranch_scc1 .Lxb_nl_3
	v_mov_b32_e32 v4, 0x3400
	global_atomic_add v6, v4, v5, s[6:7] sc0
	s_waitcnt vmcnt(0)
	v_readfirstlane_b32 s10, v6
	s_add_i32 s10, s10, 1
	s_mul_i32 s16, s16, 4
	s_cmp_lg_u32 s10, s16
	s_cbranch_scc1 .Lxb_nl_3
	v_mov_b32_e32 v4, 0x2400
	global_atomic_add v4, v5, s[6:7]
	global_atomic_add v4, v5, s[6:7] offset:256
	global_atomic_add v4, v5, s[6:7] offset:512
	global_atomic_add v4, v5, s[6:7] offset:768
	global_atomic_add v4, v5, s[6:7] offset:1024
	global_atomic_add v4, v5, s[6:7] offset:1280
	global_atomic_add v4, v5, s[6:7] offset:1536
	global_atomic_add v4, v5, s[6:7] offset:1792
	global_atomic_add v4, v5, s[6:7] offset:2048
	global_atomic_add v4, v5, s[6:7] offset:2304
	global_atomic_add v4, v5, s[6:7] offset:2560
	global_atomic_add v4, v5, s[6:7] offset:2816
	global_atomic_add v4, v5, s[6:7] offset:3072
	global_atomic_add v4, v5, s[6:7] offset:3328
	global_atomic_add v4, v5, s[6:7] offset:3584
	global_atomic_add v4, v5, s[6:7] offset:3840
	s_branch .Lxb_done_3

.LBB0_529:
	s_cmp_gt_i32 s83, 5
	s_cselect_b64 s[0:1], -1, 0
	s_and_b64 s[4:5], s[16:17], s[0:1]
	s_andn2_b64 vcc, exec, s[4:5]
	s_cbranch_vccnz .LBB0_583
	s_waitcnt vmcnt(0)
	s_waitcnt vmcnt(0) lgkmcnt(0)
	s_barrier
	s_and_saveexec_b64 s[4:5], s[94:95]
	s_cbranch_execz .LBB0_582
	v_mov_b32_e32 v1, 0x23ff0
	ds_read_b32 v2, v1
	ds_read_b32 v3, v1 offset:4
	s_add_u32 s6, s80, 0x2380000
	s_addc_u32 s7, s81, 0
	s_lshl_b32 s8, s87, 8
	s_add_i32 s9, s8, 0x1400
	s_add_i32 s8, s8, 0x2400
	v_mov_b32_e32 v4, s9
	v_mov_b32_e32 v5, 1
	global_atomic_add v6, v4, v5, s[6:7] sc0
	buffer_inv sc1
	s_waitcnt vmcnt(0) lgkmcnt(0)
	v_readfirstlane_b32 s10, v6
	v_readfirstlane_b32 s11, v2
	v_readfirstlane_b32 s16, v3
	s_add_i32 s10, s10, 1
	s_mul_i32 s11, s11, 5
	s_cmp_lg_u32 s10, s11
	s_cbranch_scc1 .Lxb_nl_4
	v_mov_b32_e32 v4, 0x3400
	global_atomic_add v6, v4, v5, s[6:7] sc0
	s_waitcnt vmcnt(0)
	v_readfirstlane_b32 s10, v6
	s_add_i32 s10, s10, 1
	s_mul_i32 s16, s16, 5
	s_cmp_lg_u32 s10, s16
	s_cbranch_scc1 .Lxb_nl_4
	v_mov_b32_e32 v4, 0x2400
	global_atomic_add v4, v5, s[6:7]
	global_atomic_add v4, v5, s[6:7] offset:256
	global_atomic_add v4, v5, s[6:7] offset:512
	global_atomic_add v4, v5, s[6:7] offset:768
	global_atomic_add v4, v5, s[6:7] offset:1024
	global_atomic_add v4, v5, s[6:7] offset:1280
	global_atomic_add v4, v5, s[6:7] offset:1536
	global_atomic_add v4, v5, s[6:7] offset:1792
	global_atomic_add v4, v5, s[6:7] offset:2048
	global_atomic_add v4, v5, s[6:7] offset:2304
	global_atomic_add v4, v5, s[6:7] offset:2560
	global_atomic_add v4, v5, s[6:7] offset:2816
	global_atomic_add v4, v5, s[6:7] offset:3072
	global_atomic_add v4, v5, s[6:7] offset:3328
	global_atomic_add v4, v5, s[6:7] offset:3584
	global_atomic_add v4, v5, s[6:7] offset:3840
	s_branch .Lxb_done_4

.LBB0_612:
	s_cmp_gt_i32 s83, 6
	s_cselect_b64 s[0:1], -1, 0
	s_and_b64 s[4:5], s[6:7], s[0:1]
	s_andn2_b64 vcc, exec, s[4:5]
	s_cbranch_vccnz .LBB0_666
	s_waitcnt vmcnt(0)
	s_waitcnt vmcnt(0) lgkmcnt(0)
	s_barrier
	s_and_saveexec_b64 s[4:5], s[94:95]
	s_cbranch_execz .LBB0_665
	v_mov_b32_e32 v1, 0x23ff0
	ds_read_b32 v2, v1
	ds_read_b32 v3, v1 offset:4
	s_add_u32 s6, s80, 0x2380000
	s_addc_u32 s7, s81, 0
	s_lshl_b32 s8, s87, 8
	s_add_i32 s9, s8, 0x1400
	s_add_i32 s8, s8, 0x2400
	v_mov_b32_e32 v4, s9
	v_mov_b32_e32 v5, 1
	global_atomic_add v6, v4, v5, s[6:7] sc0
	buffer_inv sc1
	s_waitcnt vmcnt(0) lgkmcnt(0)
	v_readfirstlane_b32 s10, v6
	v_readfirstlane_b32 s11, v2
	v_readfirstlane_b32 s16, v3
	s_add_i32 s10, s10, 1
	s_mul_i32 s11, s11, 6
	s_cmp_lg_u32 s10, s11
	s_cbranch_scc1 .Lxb_nl_5
	v_mov_b32_e32 v4, 0x3400
	global_atomic_add v6, v4, v5, s[6:7] sc0
	s_waitcnt vmcnt(0)
	v_readfirstlane_b32 s10, v6
	s_add_i32 s10, s10, 1
	s_mul_i32 s16, s16, 6
	s_cmp_lg_u32 s10, s16
	s_cbranch_scc1 .Lxb_nl_5
	v_mov_b32_e32 v4, 0x2400
	global_atomic_add v4, v5, s[6:7]
	global_atomic_add v4, v5, s[6:7] offset:256
	global_atomic_add v4, v5, s[6:7] offset:512
	global_atomic_add v4, v5, s[6:7] offset:768
	global_atomic_add v4, v5, s[6:7] offset:1024
	global_atomic_add v4, v5, s[6:7] offset:1280
	global_atomic_add v4, v5, s[6:7] offset:1536
	global_atomic_add v4, v5, s[6:7] offset:1792
	global_atomic_add v4, v5, s[6:7] offset:2048
	global_atomic_add v4, v5, s[6:7] offset:2304
	global_atomic_add v4, v5, s[6:7] offset:2560
	global_atomic_add v4, v5, s[6:7] offset:2816
	global_atomic_add v4, v5, s[6:7] offset:3072
	global_atomic_add v4, v5, s[6:7] offset:3328
	global_atomic_add v4, v5, s[6:7] offset:3584
	global_atomic_add v4, v5, s[6:7] offset:3840
	s_branch .Lxb_done_5
